# prep: wave 7 (T inversion) joins workgroup barrier B after inversion level 1 instead of after level 0 (stamped on chip: waves 0-6 2.2 us vs wave 7 1.5 us before B, 0.35 us vs 1.3 us after it)
# speedup vs baseline: 1.0160x; 1.0070x over previous
; #define WAVE_SYNC() do { asm volatile("s_waitcnt lgkmcnt(0)" ::: "memory"); __builtin_amdgcn_wave_barrier(); } while (0)
; __device__ __forceinline__ void tinv_wave(const float* Aab, bf16_t* Tm, bf16_t* TT, bf16_t* ET, bf16_t* E2T, int lane) {
;     constexpr int LD = 72;
;     const int fr = lane & 15, fq = lane >> 4;
;     const bf16x8 zf = (bf16x8){0, 0, 0, 0, 0, 0, 0, 0};
;     {
;         const u32x4 z = (u32x4){0u, 0u, 0u, 0u};
; #pragma unroll
;         for (int i = 0; i < 9; ++i) { *(u32x4*)(Tm + lane * LD + i * 8) = z; *(u32x4*)(TT + lane * LD + i * 8) = z; }
;     }
;     WAVE_SYNC();
;     {
;         const int q = fq, c = fr; const float* Ab = Aab + (16 * q) * 68 + 16 * q;
;         float d[16];
; #pragma unroll
;         for (int i = 0; i < 16; ++i) {
;             float a = (i == c) ? 1.0f : 0.0f;
; #pragma unroll
;             for (int m = 0; m < i; ++m) a -= Ab[i * 68 + m] * d[m];
;             d[i] = a;
;             if ((i & 3) == 3) __builtin_amdgcn_sched_barrier(0);
;         }
.LBB0_238:
	s_and_b64 vcc, exec, s[20:21]
	s_cbranch_vccz .LBB0_256
	v_mul_u32_u24_e32 v24, 0x48, v68
	v_lshlrev_b32_e32 v24, 1, v24
	v_add_u32_e32 v25, 0, v24
	v_add_u32_e32 v24, s66, v24
	ds_write_b128 v25, v[192:195] offset:17408
	ds_write_b128 v24, v[192:195]
	ds_write_b128 v25, v[192:195] offset:17424
	ds_write_b128 v24, v[192:195] offset:16
	ds_write_b128 v25, v[192:195] offset:17440
	ds_write_b128 v24, v[192:195] offset:32
	ds_write_b128 v25, v[192:195] offset:17456
	ds_write_b128 v24, v[192:195] offset:48
	ds_write_b128 v25, v[192:195] offset:17472
	ds_write_b128 v24, v[192:195] offset:64
	ds_write_b128 v25, v[192:195] offset:17488
	ds_write_b128 v24, v[192:195] offset:80
	ds_write_b128 v25, v[192:195] offset:17504
	ds_write_b128 v24, v[192:195] offset:96
	ds_write_b128 v25, v[192:195] offset:17520
	ds_write_b128 v24, v[192:195] offset:112
	ds_write_b128 v25, v[192:195] offset:17536
	ds_write_b128 v24, v[192:195] offset:128
	v_mul_u32_u24_e32 v24, 0x110, v141
	v_lshlrev_b32_e32 v25, 2, v141
	v_add3_u32 v69, 0, v24, v25
	s_waitcnt lgkmcnt(0)
	ds_read_b32 v27, v69 offset:272
	ds_read_b64 v[36:37], v69 offset:544
	ds_read_b96 v[24:26], v69 offset:816
	v_cmp_eq_u32_e32 vcc, 0, v185
	s_waitcnt lgkmcnt(0)
	v_mov_b32_e32 v66, v25
	v_cndmask_b32_e64 v30, 0, 1.0, vcc
	v_cmp_eq_u32_e32 vcc, 3, v185
	v_mov_b32_e32 v67, v26
	v_mov_b32_e32 v26, v36
	v_cndmask_b32_e64 v28, 0, 1.0, vcc
	v_cmp_eq_u32_e32 vcc, 1, v185
	v_fma_f32 v87, -v30, v24, v28
	s_nop 0
	v_cndmask_b32_e64 v25, 0, 1.0, vcc
	v_cmp_eq_u32_e32 vcc, 2, v185
	s_nop 1
	v_cndmask_b32_e64 v24, 0, 1.0, vcc
	v_pk_fma_f32 v[32:33], v[30:31], v[26:27], v[24:25] op_sel_hi:[0,1,1] neg_lo:[1,0,0] neg_hi:[1,0,0]
	v_mov_b32_e32 v31, v33
	ds_read_b128 v[26:29], v69 offset:1088
	ds_read_b96 v[34:36], v69 offset:1360
	ds_read_b128 v[42:45], v69 offset:1632
	v_cmp_eq_u32_e32 vcc, 4, v185
	s_waitcnt lgkmcnt(2)
	v_pk_mul_f32 v[24:25], v[30:31], v[26:27]
	v_cndmask_b32_e64 v38, 0, 1.0, vcc
	v_sub_f32_e32 v24, v38, v24
	v_cmp_eq_u32_e32 vcc, 5, v185
	v_sub_f32_e32 v126, v24, v25
	ds_read_b64 v[38:39], v69 offset:1648
	v_cndmask_b32_e64 v24, 0, 1.0, vcc
	v_cmp_eq_u32_e32 vcc, 6, v185
	s_waitcnt lgkmcnt(2)
	v_fma_f32 v143, -v30, v34, v24
	s_waitcnt lgkmcnt(1)
	v_pk_mul_f32 v[24:25], v[30:31], v[42:43]
	v_cndmask_b32_e64 v26, 0, 1.0, vcc
	v_mov_b32_e32 v88, v35
	v_sub_f32_e32 v24, v26, v24
	v_add_u32_e32 v34, 0x77c, v69
	v_add_u32_e32 v35, 0x784, v69
	v_add_u32_e32 v27, 0x55c, v69
	v_sub_f32_e32 v145, v24, v25
	ds_read_b96 v[24:26], v69 offset:1904
	ds_read2_b32 v[42:43], v27 offset1:1
	ds_read2_b32 v[90:91], v34 offset1:1
	ds_read2_b32 v[34:35], v35 offset1:1
	v_cmp_eq_u32_e32 vcc, 7, v185
	v_mov_b32_e32 v89, v36
	s_waitcnt lgkmcnt(3)
	v_mov_b32_e32 v92, v25
	v_cndmask_b32_e64 v27, 0, 1.0, vcc
	v_mov_b32_e32 v93, v26
	v_fma_f32 v190, -v30, v24, v27
	ds_read_b128 v[46:49], v69 offset:2176
	ds_read_b128 v[24:27], v69 offset:2192
	ds_read_b96 v[54:56], v69 offset:2448
	ds_read_b128 v[50:53], v69 offset:2720
	v_cmp_eq_u32_e32 vcc, 8, v185
	v_add_u32_e32 v58, 0x9a4, v69
	s_waitcnt lgkmcnt(3)
	v_pk_mul_f32 v[46:47], v[30:31], v[46:47]
	v_cndmask_b32_e64 v36, 0, 1.0, vcc
	v_sub_f32_e32 v36, v36, v46
	v_cmp_eq_u32_e32 vcc, 9, v185
	v_sub_f32_e32 v191, v36, v47
	s_waitcnt lgkmcnt(0)
	v_pk_mul_f32 v[50:51], v[30:31], v[50:51]
	v_cndmask_b32_e64 v36, 0, 1.0, vcc
	v_cmp_eq_u32_e32 vcc, 10, v185
	v_fma_f32 v196, -v30, v54, v36
	v_add_u32_e32 v59, 0x9ac, v69
	v_cndmask_b32_e64 v54, 0, 1.0, vcc
	v_sub_f32_e32 v50, v54, v50
	v_add_u32_e32 v60, 0xbbc, v69
	v_mov_b32_e32 v46, v55
	v_mov_b32_e32 v47, v56
	v_add_u32_e32 v36, 0x99c, v69
	v_sub_f32_e32 v197, v50, v51
	v_add_u32_e32 v61, 0xbc4, v69
	v_add_u32_e32 v62, 0xbcc, v69
	v_add_u32_e32 v63, 0xbd4, v69
	ds_read_b64 v[50:51], v69 offset:2752
	ds_read_b128 v[54:57], v69 offset:2736
	ds_read2_b32 v[94:95], v60 offset1:1
	ds_read2_b32 v[96:97], v61 offset1:1
	ds_read2_b32 v[98:99], v59 offset1:1
	ds_read2_b32 v[100:101], v58 offset1:1
	ds_read_b96 v[58:60], v69 offset:2992
	ds_read2_b32 v[102:103], v36 offset1:1
	ds_read2_b32 v[104:105], v62 offset1:1
	ds_read2_b32 v[106:107], v63 offset1:1
	v_cmp_eq_u32_e32 vcc, 11, v185
	s_waitcnt lgkmcnt(3)
	v_mov_b32_e32 v108, v59
	v_mov_b32_e32 v109, v60
	v_cndmask_b32_e64 v36, 0, 1.0, vcc
	v_fma_f32 v198, -v30, v58, v36
	ds_read_b128 v[58:61], v69 offset:3264
	ds_read_b128 v[62:65], v69 offset:3280
	ds_read_b128 v[70:73], v69 offset:3296
	ds_read_b96 v[74:76], v69 offset:3536
	v_cmp_eq_u32_e32 vcc, 12, v185
	v_add_u32_e32 v83, 0x100c, v69
	s_waitcnt lgkmcnt(3)
	v_pk_mul_f32 v[58:59], v[30:31], v[58:59]
	v_cndmask_b32_e64 v36, 0, 1.0, vcc
	v_cmp_eq_u32_e32 vcc, 13, v185
	v_sub_f32_e32 v31, v36, v58
	v_sub_f32_e32 v31, v31, v59
	v_cndmask_b32_e64 v36, 0, 1.0, vcc
	s_waitcnt lgkmcnt(0)
	v_mov_b32_e32 v58, v75
	v_mov_b32_e32 v59, v76
	v_fma_f32 v199, -v30, v74, v36
	ds_read_b128 v[74:77], v69 offset:3808
	ds_read_b96 v[84:86], v69 offset:4080
	ds_read_b128 v[78:81], v69 offset:3824
	v_cmp_eq_u32_e32 vcc, 14, v185
	v_add_u32_e32 v36, 0xddc, v69
	v_fma_f32 v189, -v33, v37, v32
	v_cndmask_b32_e64 v82, 0, 1.0, vcc
	s_waitcnt lgkmcnt(2)
	v_fma_f32 v74, -v30, v74, v82
	v_cndmask_b32_e64 v82, 0, 1.0, s[18:19]
	v_fma_f32 v200, -v33, v75, v74
	ds_read2_b32 v[74:75], v36 offset1:1
	s_waitcnt lgkmcnt(2)
; __device__ __forceinline__ void tinv_wave(const float* Aab, bf16_t* Tm, bf16_t* TT, bf16_t* ET, bf16_t* E2T, int lane) {
;     ...
; #pragma unroll
;         for (int i = 0; i < 16; ++i) {
;             float a = (i == c) ? 1.0f : 0.0f;
; #pragma unroll
;             for (int m = 0; m < i; ++m) a -= Ab[i * 68 + m] * d[m];
;             d[i] = a;
;             if ((i & 3) == 3) __builtin_amdgcn_sched_barrier(0);
;         }
	v_fma_f32 v36, -v30, v84, v82
	v_fma_f32 v201, -v33, v85, v36
	v_add_u32_e32 v36, 0xffc, v69
	v_add_u32_e32 v82, 0x1004, v69
	v_add_u32_e32 v84, 0x1014, v69
	ds_read2_b32 v[110:111], v36 offset1:1
	ds_read2_b32 v[112:113], v82 offset1:1
	ds_read2_b32 v[114:115], v83 offset1:1
	ds_read2_b32 v[116:117], v84 offset1:1
	v_add_u32_e32 v36, 0x101c, v69
	v_mov_b32_e32 v188, v33
	ds_read2_b32 v[118:119], v36 offset1:1
	v_pk_mul_f32 v[36:37], v[188:189], v[66:67]
	v_pk_mul_f32 v[66:67], v[188:189], v[88:89]
	v_add_u32_e32 v154, 0xde4, v69
	v_add_u32_e32 v152, 0xdec, v69
	v_add_u32_e32 v150, 0xdf4, v69
	v_add_u32_e32 v148, 0xdfc, v69
	v_sub_f32_e32 v32, v87, v36
	v_sub_f32_e32 v36, v143, v66
	v_add_u32_e32 v202, 0x1024, v69
	ds_read_b64 v[146:147], v69 offset:3856
	ds_read_b128 v[82:85], v69 offset:3840
	ds_read2_b32 v[148:149], v148 offset1:1
	ds_read2_b32 v[150:151], v150 offset1:1
	ds_read2_b32 v[152:153], v152 offset1:1
	ds_read2_b32 v[154:155], v154 offset1:1
	v_sub_f32_e32 v69, v36, v67
	v_pk_mul_f32 v[66:67], v[188:189], v[92:93]
	v_pk_mul_f32 v[46:47], v[188:189], v[46:47]
	v_sub_f32_e32 v36, v190, v66
	v_sub_f32_e32 v66, v36, v67
	v_sub_f32_e32 v36, v196, v46
	v_sub_f32_e32 v67, v36, v47
	v_pk_mul_f32 v[46:47], v[188:189], v[108:109]
	v_pk_mul_f32 v[58:59], v[188:189], v[58:59]
	v_sub_f32_e32 v36, v198, v46
	v_sub_f32_e32 v87, v36, v47
	v_sub_f32_e32 v47, v32, v37
	v_mov_b32_e32 v46, v189
	v_pk_mul_f32 v[28:29], v[46:47], v[28:29]
	v_pk_mul_f32 v[36:37], v[46:47], v[60:61]
	v_sub_f32_e32 v28, v126, v28
	v_pk_mul_f32 v[48:49], v[46:47], v[48:49]
	v_pk_mul_f32 v[52:53], v[46:47], v[52:53]
	v_pk_mul_f32 v[44:45], v[46:47], v[44:45]
	v_sub_f32_e32 v29, v28, v29
	v_mov_b32_e32 v28, v47
	v_sub_f32_e32 v31, v31, v36
	v_sub_f32_e32 v32, v199, v58
	v_sub_f32_e32 v36, v191, v48
	v_sub_f32_e32 v48, v197, v52
	v_sub_f32_e32 v44, v145, v44
	v_pk_mul_f32 v[42:43], v[28:29], v[42:43]
	v_sub_f32_e32 v32, v32, v59
	v_pk_mul_f32 v[58:59], v[46:47], v[76:77]
	v_sub_f32_e32 v46, v44, v45
	v_sub_f32_e32 v52, v36, v49
	v_sub_f32_e32 v53, v48, v53
	v_sub_f32_e32 v31, v31, v37
	s_waitcnt lgkmcnt(11)
	v_pk_mul_f32 v[36:37], v[28:29], v[74:75]
	v_pk_mul_f32 v[44:45], v[28:29], v[102:103]
	v_sub_f32_e32 v42, v69, v42
	v_pk_mul_f32 v[48:49], v[28:29], v[90:91]
	v_sub_f32_e32 v58, v200, v58
	v_sub_f32_e32 v32, v32, v36
	v_sub_f32_e32 v36, v67, v44
	v_sub_f32_e32 v44, v66, v48
	v_sub_f32_e32 v43, v42, v43
	v_mov_b32_e32 v42, v29
	v_sub_f32_e32 v58, v58, v59
	v_sub_f32_e32 v59, v44, v49
	v_sub_f32_e32 v61, v36, v45
	v_pk_mul_f32 v[44:45], v[28:29], v[94:95]
	v_pk_mul_f32 v[38:39], v[42:43], v[38:39]
	v_fma_f32 v60, -v189, v86, v201
	v_sub_f32_e32 v36, v87, v44
	s_waitcnt lgkmcnt(10)
	v_pk_mul_f32 v[48:49], v[28:29], v[110:111]
	v_pk_mul_f32 v[24:25], v[42:43], v[24:25]
	v_sub_f32_e32 v38, v46, v38
	v_sub_f32_e32 v66, v36, v45
	v_sub_f32_e32 v32, v32, v37
	v_pk_mul_f32 v[36:37], v[42:43], v[78:79]
	v_sub_f32_e32 v28, v60, v48
	v_sub_f32_e32 v24, v52, v24
	v_sub_f32_e32 v39, v38, v39
	v_mov_b32_e32 v38, v43
	v_pk_mul_f32 v[44:45], v[42:43], v[62:63]
	v_sub_f32_e32 v36, v58, v36
	v_sub_f32_e32 v28, v28, v49
	v_pk_mul_f32 v[48:49], v[42:43], v[54:55]
	v_sub_f32_e32 v42, v24, v25
	s_waitcnt lgkmcnt(0)
; __device__ __forceinline__ unsigned pk_bf16(float lo, float hi) { const f32x2 v = (f32x2){lo, hi}; const bf16v2 b = __builtin_convertvector(v, bf16v2); return __builtin_bit_cast(unsigned, b); }
; __device__ __forceinline__ bf16_t f2bf(float f) { return (bf16_t)(pk_bf16(f, 0.f) & 0xffffu); }
; #define LDS_BARRIER() do { asm volatile("s_waitcnt lgkmcnt(0)" ::: "memory"); __builtin_amdgcn_s_barrier(); asm volatile("" ::: "memory"); } while (0)
; #define WAVE_SYNC() do { asm volatile("s_waitcnt lgkmcnt(0)" ::: "memory"); __builtin_amdgcn_wave_barrier(); } while (0)
; #define P() (*(const Params*)(cp = cp_launder(cp)))
; __device__ __forceinline__ void tinv_wave(const float* Aab, bf16_t* Tm, bf16_t* TT, bf16_t* ET, bf16_t* E2T, int lane) {
;     ...
; #pragma unroll
;         for (int i = 0; i < 16; ++i) {
;             float a = (i == c) ? 1.0f : 0.0f;
; #pragma unroll
;             for (int m = 0; m < i; ++m) a -= Ab[i * 68 + m] * d[m];
;             d[i] = a;
;             if ((i & 3) == 3) __builtin_amdgcn_sched_barrier(0);
;         }
;         u32x4 lo, hi;
;         lo.x = pk_bf16(d[0], d[1]); lo.y = pk_bf16(d[2], d[3]); lo.z = pk_bf16(d[4], d[5]); lo.w = pk_bf16(d[6], d[7]);
;         hi.x = pk_bf16(d[8], d[9]); hi.y = pk_bf16(d[10], d[11]); hi.z = pk_bf16(d[12], d[13]); hi.w = pk_bf16(d[14], d[15]);
;         *(u32x4*)(TT + (16 * q + c) * LD + 16 * q) = lo; *(u32x4*)(TT + (16 * q + c) * LD + 16 * q + 8) = hi;
; #pragma unroll
;         for (int i = 0; i < 16; ++i) Tm[(16 * q + i) * LD + 16 * q + c] = f2bf(d[i]);
;     }
;     WAVE_SYNC();
;     LDS_BARRIER();
; #pragma unroll
;     for (int P = 0; P < 2; ++P) {
;         const int lo = 2 * P, hi = 2 * P + 1;
;         const bf16x8 a = fq < 2 ? cvt_frag8(Aab + (16 * hi + fr) * 68 + 16 * lo + 8 * fq) : zf;
;         const bf16x8 b = fq < 2 ? *(const bf16x8*)(TT + (16 * lo + fr) * LD + 16 * lo + 8 * fq) : zf;
	v_pk_mul_f32 v[24:25], v[38:39], v[154:155]
	v_pk_mul_f32 v[34:35], v[38:39], v[34:35]
	v_sub_f32_e32 v31, v31, v44
	v_sub_f32_e32 v44, v53, v48
	v_sub_f32_e32 v24, v32, v24
	v_sub_f32_e32 v32, v36, v37
	v_pk_mul_f32 v[36:37], v[38:39], v[100:101]
	v_sub_f32_e32 v34, v59, v34
	v_sub_f32_e32 v46, v44, v49
	v_sub_f32_e32 v31, v31, v45
	v_sub_f32_e32 v36, v61, v36
	v_sub_f32_e32 v45, v34, v35
	v_mov_b32_e32 v44, v39
	v_sub_f32_e32 v52, v36, v37
	v_pk_mul_f32 v[36:37], v[38:39], v[96:97]
	v_pk_mul_f32 v[26:27], v[44:45], v[26:27]
	v_sub_f32_e32 v36, v66, v36
	v_sub_f32_e32 v26, v42, v26
	v_sub_f32_e32 v53, v36, v37
	v_pk_mul_f32 v[34:35], v[44:45], v[64:65]
	v_pk_mul_f32 v[36:37], v[38:39], v[112:113]
	v_sub_f32_e32 v49, v26, v27
	v_mov_b32_e32 v48, v45
	v_sub_f32_e32 v31, v31, v34
	v_sub_f32_e32 v34, v24, v25
	v_pk_mul_f32 v[24:25], v[44:45], v[80:81]
	v_sub_f32_e32 v28, v28, v36
	v_pk_mul_f32 v[26:27], v[48:49], v[152:153]
	v_sub_f32_e32 v24, v32, v24
	v_sub_f32_e32 v28, v28, v37
	v_pk_mul_f32 v[36:37], v[44:45], v[56:57]
	v_sub_f32_e32 v31, v31, v35
	v_sub_f32_e32 v26, v34, v26
	v_pk_mul_f32 v[34:35], v[48:49], v[104:105]
	v_sub_f32_e32 v32, v46, v36
	v_sub_f32_e32 v36, v24, v25
	v_pk_mul_f32 v[24:25], v[48:49], v[98:99]
	v_sub_f32_e32 v34, v53, v34
	v_sub_f32_e32 v32, v32, v37
	v_sub_f32_e32 v24, v52, v24
	v_sub_f32_e32 v37, v34, v35
	v_pk_mul_f32 v[34:35], v[48:49], v[114:115]
	v_sub_f32_e32 v53, v24, v25
	v_mov_b32_e32 v52, v49
	v_sub_f32_e32 v28, v28, v34
	v_sub_f32_e32 v28, v28, v35
	v_pk_mul_f32 v[34:35], v[52:53], v[50:51]
	v_pk_mul_f32 v[24:25], v[52:53], v[70:71]
	v_sub_f32_e32 v32, v32, v34
	v_sub_f32_e32 v24, v31, v24
	v_sub_f32_e32 v31, v26, v27
	v_pk_mul_f32 v[26:27], v[52:53], v[82:83]
	v_sub_f32_e32 v51, v32, v35
	v_mov_b32_e32 v50, v53
	v_sub_f32_e32 v26, v36, v26
	v_sub_f32_e32 v34, v24, v25
	v_pk_mul_f32 v[24:25], v[50:51], v[150:151]
	v_mov_b32_e32 v54, v51
	v_sub_f32_e32 v24, v31, v24
	v_sub_f32_e32 v31, v26, v27
	v_pk_mul_f32 v[26:27], v[50:51], v[106:107]
	v_sub_f32_e32 v32, v24, v25
	v_sub_f32_e32 v26, v37, v26
	v_sub_f32_e32 v55, v26, v27
	v_pk_mul_f32 v[26:27], v[54:55], v[72:73]
	v_mov_b32_e32 v56, v55
	v_sub_f32_e32 v26, v34, v26
	v_sub_f32_e32 v57, v26, v27
	v_pk_mul_f32 v[26:27], v[56:57], v[148:149]
	v_pk_mul_f32 v[24:25], v[54:55], v[84:85]
	v_sub_f32_e32 v26, v32, v26
	v_sub_f32_e32 v59, v26, v27
	ds_read2_b32 v[26:27], v202 offset1:1
	v_sub_f32_e32 v24, v31, v24
	v_pk_mul_f32 v[34:35], v[50:51], v[116:117]
	v_mov_b32_e32 v58, v57
	v_sub_f32_e32 v28, v28, v34
	v_sub_f32_e32 v31, v24, v25
	v_pk_mul_f32 v[24:25], v[58:59], v[146:147]
	v_sub_f32_e32 v28, v28, v35
	v_sub_f32_e32 v24, v31, v24
	v_pk_mul_f32 v[34:35], v[56:57], v[118:119]
	v_sub_f32_e32 v61, v24, v25
	v_sub_f32_e32 v28, v28, v34
	v_mov_b32_e32 v60, v59
	v_sub_f32_e32 v28, v28, v35
	s_waitcnt lgkmcnt(0)
	v_pk_mul_f32 v[24:25], v[60:61], v[26:27]
	s_nop 0
	v_sub_f32_e32 v24, v28, v24
	v_sub_f32_e32 v28, v24, v25
	v_mul_u32_u24_e32 v31, 0x90, v68
	v_lshlrev_b32_e32 v32, 1, v141
	v_cvt_pk_bf16_f32 v24, v30, v33
	v_cvt_pk_bf16_f32 v25, v189, v47
	v_cvt_pk_bf16_f32 v26, v29, v43
	v_cvt_pk_bf16_f32 v27, v39, v45
	v_add3_u32 v31, s66, v31, v32
	v_cvt_pk_bf16_f32 v34, v49, v53
	v_cvt_pk_bf16_f32 v35, v51, v55
	v_cvt_pk_bf16_f32 v36, v57, v59
	v_cvt_pk_bf16_f32 v37, v61, v28
	ds_write_b128 v31, v[24:27]
	ds_write_b128 v31, v[34:37] offset:16
	v_lshlrev_b32_e32 v24, 1, v185
	v_add3_u32 v24, 0, v32, v24
	v_cvt_pk_bf16_f32 v25, v30, s0
	v_mad_u32_u24 v26, v141, s50, v24
	ds_write_b16 v26, v25 offset:17408
	v_cvt_pk_bf16_f32 v25, v33, s0
	ds_write_b16 v26, v25 offset:17552
	v_cvt_pk_bf16_f32 v25, v189, s0
	ds_write_b16 v26, v25 offset:17696
	v_cvt_pk_bf16_f32 v25, v47, s0
	ds_write_b16 v26, v25 offset:17840
	v_cvt_pk_bf16_f32 v25, v29, s0
	ds_write_b16 v26, v25 offset:17984
	v_cvt_pk_bf16_f32 v25, v43, s0
	ds_write_b16 v26, v25 offset:18128
	v_cvt_pk_bf16_f32 v25, v39, s0
	ds_write_b16 v26, v25 offset:18272
	v_cvt_pk_bf16_f32 v25, v45, s0
	ds_write_b16 v26, v25 offset:18416
	v_cvt_pk_bf16_f32 v25, v49, s0
	ds_write_b16 v26, v25 offset:18560
	v_cvt_pk_bf16_f32 v25, v53, s0
	ds_write_b16 v26, v25 offset:18704
	v_cvt_pk_bf16_f32 v25, v51, s0
	ds_write_b16 v26, v25 offset:18848
	v_cvt_pk_bf16_f32 v25, v55, s0
	ds_write_b16 v26, v25 offset:18992
	v_cvt_pk_bf16_f32 v25, v57, s0
	ds_write_b16 v26, v25 offset:19136
	v_cvt_pk_bf16_f32 v25, v59, s0
	ds_write_b16 v26, v25 offset:19280
	v_cvt_pk_bf16_f32 v25, v61, s0
	ds_write_b16 v26, v25 offset:19424
	v_or_b32_e32 v26, 15, v68
	v_cvt_pk_bf16_f32 v25, v28, s0
	v_mad_u32_u24 v24, v26, s50, v24
	ds_write_b16 v24, v25 offset:17408
	s_waitcnt lgkmcnt(0)
	s_waitcnt lgkmcnt(0)
	v_cmp_gt_u32_e32 vcc, 32, v68
	v_lshlrev_b32_e32 v35, 5, v137
	v_mov_b32_e32 v24, 0
	v_mov_b32_e32 v28, 0
	v_mov_b32_e32 v29, 0
	v_mov_b32_e32 v30, 0
	v_mov_b32_e32 v31, 0
	s_and_saveexec_b64 s[18:19], vcc
	s_cbranch_execz .LBB0_241
	v_or_b32_e32 v25, 16, v68
	v_mul_u32_u24_e32 v25, 0x110, v25
	v_add3_u32 v25, 0, v25, v35
	ds_read_b128 v[28:31], v25
	ds_read_b128 v[36:39], v25 offset:16
	s_waitcnt lgkmcnt(1)
	v_cvt_pk_bf16_f32 v28, v28, v29
	v_cvt_pk_bf16_f32 v29, v30, v31
	s_waitcnt lgkmcnt(0)
	v_cvt_pk_bf16_f32 v30, v36, v37
	v_cvt_pk_bf16_f32 v31, v38, v39

; __device__ __forceinline__ bf16_t f2bf(float f) { return (bf16_t)(pk_bf16(f, 0.f) & 0xffffu); }
; __device__ __forceinline__ void st_bf4(bf16_t* p, f32x4 v) { u32x2 u; u.x = pk_bf16(v[0], v[1]); u.y = pk_bf16(v[2], v[3]); *(u32x2*)p = u; }
; __device__ __forceinline__ void tinv_wave(const float* Aab, bf16_t* Tm, bf16_t* TT, bf16_t* ET, bf16_t* E2T, int lane) {
;     ...
;     for (int P = 0; P < 2; ++P) {
;         const int lo = 2 * P, hi = 2 * P + 1;
;         const bf16x8 a = fq < 2 ? cvt_frag8(Aab + (16 * hi + fr) * 68 + 16 * lo + 8 * fq) : zf;
;         const bf16x8 b = fq < 2 ? *(const bf16x8*)(TT + (16 * lo + fr) * LD + 16 * lo + 8 * fq) : zf;
;         const f32x4 e = MFMA16(a, b, ((f32x4){0.f, 0.f, 0.f, 0.f}));
;         st_bf4(ET + (P * 16 + fr) * 24 + 4 * fq, e);
;     }
;     WAVE_SYNC();
; #pragma unroll
;     for (int P = 0; P < 2; ++P) {
;         const int lo = 2 * P, hi = 2 * P + 1;
;         const bf16x8 a = fq < 2 ? *(const bf16x8*)(Tm + (16 * hi + fr) * LD + 16 * hi + 8 * fq) : zf;
;         const bf16x8 b = fq < 2 ? *(const bf16x8*)(ET + (P * 16 + fr) * 24 + 8 * fq) : zf;
;         const f32x4 t = -MFMA16(a, b, ((f32x4){0.f, 0.f, 0.f, 0.f}));
;         st_bf4(TT + (16 * lo + fr) * LD + 16 * hi + 4 * fq, t);
; #pragma unroll
;         for (int j = 0; j < 4; ++j) Tm[(16 * hi + 4 * fq + j) * LD + 16 * lo + fr] = f2bf(t[j]);
;     }
;     WAVE_SYNC();
; #pragma unroll
;     for (int mi = 0; mi < 2; ++mi) {
;         const bf16x8 a = cvt_frag8(Aab + (32 + 16 * mi + fr) * 68 + 8 * fq);
; #pragma unroll
;         for (int nc = 0; nc < 2; ++nc) {
;             const bf16x8 b = *(const bf16x8*)(TT + (16 * nc + fr) * LD + 8 * fq);
;             const f32x4 e = MFMA16(a, b, ((f32x4){0.f, 0.f, 0.f, 0.f}));
;             st_bf4(E2T + (16 * nc + fr) * 40 + 16 * mi + 4 * fq, e);
;         }
;     }
;     WAVE_SYNC();
; #pragma unroll
;     for (int mi = 0; mi < 2; ++mi) {
;         const bf16x8 a = *(const bf16x8*)(Tm + (32 + 16 * mi + fr) * LD + 32 + 8 * fq);
; #pragma unroll
;         for (int nc = 0; nc < 2; ++nc) {
;             const bf16x8 b = *(const bf16x8*)(E2T + (16 * nc + fr) * 40 + 8 * fq);
;             const f32x4 t = -MFMA16(a, b, ((f32x4){0.f, 0.f, 0.f, 0.f}));
; #pragma unroll
;             for (int j = 0; j < 4; ++j) Tm[(32 + 16 * mi + 4 * fq + j) * LD + 16 * nc + fr] = f2bf(t[j]);
;         }
;     }
;     LDS_BARRIER();
.LBB0_245:
	s_or_b64 exec, exec, s[18:19]
	v_mov_b32_e32 v25, 0
	v_mov_b32_e32 v26, 0
	v_mov_b32_e32 v27, 0
	s_and_saveexec_b64 s[18:19], vcc
	ds_read_b128 v[24:27], v37 offset:4672
	s_or_b64 exec, exec, s[18:19]
	s_waitcnt lgkmcnt(0)
	v_mfma_f32_16x16x32_bf16 v[24:27], v[28:31], v[24:27], 0
	v_mul_u32_u24_e32 v37, 48, v185
	v_add_u32_e32 v28, v37, v33
	v_or_b32_e32 v35, 16, v185
	v_mov_b32_e32 v29, 0
	v_mov_b32_e32 v30, 0
	s_nop 2
	v_cvt_pk_bf16_f32 v24, v24, v25
	v_cvt_pk_bf16_f32 v25, v26, v27
	ds_write_b64 v28, v[24:25] offset:768
	s_waitcnt lgkmcnt(0)
	v_mov_b32_e32 v24, 0
	v_mov_b32_e32 v28, 0
	v_mov_b32_e32 v31, 0
	s_and_saveexec_b64 s[18:19], vcc
	v_mul_u32_u24_e32 v25, 0x90, v35
	v_add3_u32 v25, 0, v25, v34
	ds_read_b128 v[28:31], v25 offset:17440
	s_or_b64 exec, exec, s[18:19]
	v_add_u32_e32 v25, s67, v34
	v_add_u32_e32 v38, v25, v37
	v_mov_b32_e32 v25, 0
	v_mov_b32_e32 v26, 0
	v_mov_b32_e32 v27, 0
	s_and_saveexec_b64 s[18:19], vcc
	ds_read_b128 v[24:27], v38
	s_or_b64 exec, exec, s[18:19]
	s_waitcnt lgkmcnt(0)
	v_mfma_f32_16x16x32_bf16 v[24:27], v[28:31], v[24:27], 0
	v_lshlrev_b32_e32 v39, 1, v139
	v_lshl_add_u32 v37, v185, 1, 0
	v_add3_u32 v39, s66, v32, v39
	v_mul_u32_u24_e32 v36, 0x90, v36
	v_mov_b32_e32 v31, 0
	s_nop 2
	v_xor_b32_e32 v28, 0x80000000, v24
	v_xor_b32_e32 v29, 0x80000000, v25
	v_cvt_pk_bf16_f32 v28, v28, v29
	v_xor_b32_e32 v29, 0x80000000, v26
	v_xor_b32_e32 v30, 0x80000000, v27
	v_cvt_pk_bf16_f32 v29, v29, v30
	ds_write_b64 v39, v[28:29] offset:32
	v_cvt_pk_bf16_f32 v24, -v24, s0
	v_mad_u32_u24 v28, v137, s68, v37
	ds_write_b16 v28, v24 offset:19712
	v_cvt_pk_bf16_f32 v24, -v25, s0
	ds_write_b16 v28, v24 offset:19856
	v_cvt_pk_bf16_f32 v24, -v26, s0
	ds_write_b16 v28, v24 offset:20000
	v_cvt_pk_bf16_f32 v24, -v27, s0
	ds_write_b16 v28, v24 offset:20144
	v_mov_b32_e32 v24, 0
	v_mov_b32_e32 v28, 0
	v_mov_b32_e32 v29, 0
	v_mov_b32_e32 v30, 0
	s_and_saveexec_b64 s[18:19], vcc
	v_add3_u32 v25, 0, v36, v34
	ds_read_b128 v[28:31], v25 offset:17504
	s_or_b64 exec, exec, s[18:19]
	v_mov_b32_e32 v25, 0
	v_mov_b32_e32 v26, 0
	v_mov_b32_e32 v27, 0
	s_and_saveexec_b64 s[18:19], vcc
	ds_read_b128 v[24:27], v38 offset:768
	s_or_b64 exec, exec, s[18:19]
	s_waitcnt lgkmcnt(0)
	v_mfma_f32_16x16x32_bf16 v[24:27], v[28:31], v[24:27], 0
	v_mul_u32_u24_e32 v34, 0x240, v137
	v_add_u32_e32 v37, v37, v34
	v_mad_u32_u24 v38, v185, s48, 0
	v_lshl_add_u32 v34, v41, 2, v38
	v_mad_u32_u24 v46, v185, s69, v33
	s_nop 2
	v_xor_b32_e32 v28, 0x80000000, v24
	v_xor_b32_e32 v29, 0x80000000, v25
	v_xor_b32_e32 v30, 0x80000000, v26
	v_cvt_pk_bf16_f32 v28, v28, v29
	v_xor_b32_e32 v29, 0x80000000, v27
	v_cvt_pk_bf16_f32 v29, v30, v29
	v_cvt_pk_bf16_f32 v24, -v24, s0
	ds_write_b64 v39, v[28:29] offset:4704
	ds_write_b16 v37, v24 offset:24384
	v_cvt_pk_bf16_f32 v24, -v25, s0
	ds_write_b16 v37, v24 offset:24528
	v_cvt_pk_bf16_f32 v24, -v26, s0
	ds_write_b16 v37, v24 offset:24672
	v_cvt_pk_bf16_f32 v24, -v27, s0
	ds_write_b16 v37, v24 offset:24816
	s_waitcnt lgkmcnt(0)
	s_barrier
	ds_read_b128 v[24:27], v34 offset:8704
	ds_read_b128 v[28:31], v34 offset:8720
	v_add_u32_e32 v39, s66, v40
	v_add_u32_e32 v32, v39, v32
	ds_read_b128 v[42:45], v32
	s_waitcnt lgkmcnt(2)
	v_cvt_pk_bf16_f32 v24, v24, v25
	v_cvt_pk_bf16_f32 v25, v26, v27
	s_waitcnt lgkmcnt(1)
	v_cvt_pk_bf16_f32 v26, v28, v29
	v_cvt_pk_bf16_f32 v27, v30, v31
	s_waitcnt lgkmcnt(0)
	s_nop 0
	v_mfma_f32_16x16x32_bf16 v[28:31], v[24:27], v[42:45], 0
	s_nop 7
	v_cvt_pk_bf16_f32 v28, v28, v29
	v_cvt_pk_bf16_f32 v29, v30, v31
	ds_write_b64 v46, v[28:29]
	v_mad_u32_u24 v28, v35, s50, v39
	ds_read_b128 v[28:31], v28
	v_mad_u32_u24 v39, v185, s69, v184
	s_waitcnt lgkmcnt(0)
	v_mfma_f32_16x16x32_bf16 v[24:27], v[24:27], v[28:31], 0
	v_add_u32_e32 v47, v33, v39
	s_nop 6
	v_cvt_pk_bf16_f32 v24, v24, v25
	v_cvt_pk_bf16_f32 v25, v26, v27
	ds_write_b64 v47, v[24:25]
	ds_read_b128 v[24:27], v34 offset:13056
	ds_read_b128 v[32:35], v34 offset:13072
	s_waitcnt lgkmcnt(1)
	v_cvt_pk_bf16_f32 v24, v24, v25
	v_cvt_pk_bf16_f32 v25, v26, v27
	s_waitcnt lgkmcnt(0)
	v_cvt_pk_bf16_f32 v26, v32, v33
	v_cvt_pk_bf16_f32 v27, v34, v35
	s_nop 1
	v_mfma_f32_16x16x32_bf16 v[32:35], v[24:27], v[42:45], 0
	v_mfma_f32_16x16x32_bf16 v[24:27], v[24:27], v[28:31], 0
	s_nop 6
	v_cvt_pk_bf16_f32 v32, v32, v33
	v_cvt_pk_bf16_f32 v33, v34, v35
	ds_write_b64 v46, v[32:33] offset:32
	v_cvt_pk_bf16_f32 v24, v24, v25
	v_cvt_pk_bf16_f32 v25, v26, v27
	ds_write_b64 v47, v[24:25] offset:32
	v_lshlrev_b32_e32 v24, 7, v185
	v_sub_u32_e32 v24, v38, v24
	v_add_u32_e32 v24, v24, v40
	s_waitcnt lgkmcnt(0)
	ds_read_b128 v[24:27], v24 offset:22080
	v_add_u32_e32 v38, s67, v40
	v_mad_u32_u24 v28, v185, s69, v38
	ds_read_b128 v[28:31], v28
	s_waitcnt lgkmcnt(0)
	v_mfma_f32_16x16x32_bf16 v[32:35], v[24:27], v[28:31], 0
	s_nop 7
	v_cvt_pk_bf16_f32 v32, -v32, s0
	ds_write_b16 v37, v32 offset:22016
	v_cvt_pk_bf16_f32 v32, -v33, s0
	ds_write_b16 v37, v32 offset:22160
	v_cvt_pk_bf16_f32 v32, -v34, s0
	ds_write_b16 v37, v32 offset:22304
	v_cvt_pk_bf16_f32 v32, -v35, s0
	ds_write_b16 v37, v32 offset:22448
	v_add_u32_e32 v32, v38, v39
	ds_read_b128 v[32:35], v32
	s_waitcnt lgkmcnt(0)
	v_mfma_f32_16x16x32_bf16 v[24:27], v[24:27], v[32:35], 0
	s_nop 7
	v_cvt_pk_bf16_f32 v24, -v24, s0
	ds_write_b16 v37, v24 offset:22048
	v_cvt_pk_bf16_f32 v24, -v25, s0
	ds_write_b16 v37, v24 offset:22192
	v_cvt_pk_bf16_f32 v24, -v26, s0
	ds_write_b16 v37, v24 offset:22336
	v_cvt_pk_bf16_f32 v24, -v27, s0
	ds_write_b16 v37, v24 offset:22480
	v_add3_u32 v24, 0, v36, v40
	ds_read_b128 v[24:27], v24 offset:17472
	s_waitcnt lgkmcnt(0)
	v_mfma_f32_16x16x32_bf16 v[28:31], v[24:27], v[28:31], 0
	s_nop 7
	v_cvt_pk_bf16_f32 v28, -v28, s0
	v_mfma_f32_16x16x32_bf16 v[24:27], v[24:27], v[32:35], 0
	v_cvt_pk_bf16_f32 v29, -v29, s0
	ds_write_b16 v37, v28 offset:24320
	ds_write_b16 v37, v29 offset:24464
	v_cvt_pk_bf16_f32 v28, -v30, s0
	ds_write_b16 v37, v28 offset:24608
	s_nop 2
	v_cvt_pk_bf16_f32 v24, -v24, s0
	ds_write_b16 v37, v24 offset:24352
	v_cvt_pk_bf16_f32 v24, -v25, s0
	ds_write_b16 v37, v24 offset:24496
	v_cvt_pk_bf16_f32 v24, -v26, s0
	v_cvt_pk_bf16_f32 v28, -v31, s0
	ds_write_b16 v37, v24 offset:24640
	v_cvt_pk_bf16_f32 v24, -v27, s0
	ds_write_b16 v37, v28 offset:24752
	ds_write_b16 v37, v24 offset:24784
	s_waitcnt lgkmcnt(0)
	s_barrier
